# gemm_in: the peeled last K step reads its LDS fragments several ahead into spare VGPR quads with counted lgkmcnt instead of read-wait-MFMA one at a time
# speedup vs baseline: 1.0055x; 1.0041x over previous
.LBB0_300:
	s_add_i32 s1, s13, 0x8000
	s_and_b32 s41, s1, 0x8000
	v_add_u32_e32 v122, s41, v67
	s_waitcnt vmcnt(0)
	v_add_u32_e32 v123, 0x4000, v122
	v_readfirstlane_b32 s41, v122
	s_waitcnt lgkmcnt(0)
	s_barrier
	s_mov_b32 m0, s41
	v_lshl_add_u64 v[120:121], v[100:101], 0, s[42:43]
	global_load_lds_dwordx4 v[120:121], off
	s_add_u32 m0, s41, 0x4000
	v_lshl_add_u64 v[120:121], v[108:109], 0, s[42:43]
	global_load_lds_dwordx4 v[120:121], off
	s_add_u32 m0, s41, 0x1000
	v_lshl_add_u64 v[120:121], v[102:103], 0, s[42:43]
	global_load_lds_dwordx4 v[120:121], off
	s_add_u32 m0, s41, 0x5000
	v_lshl_add_u64 v[120:121], v[110:111], 0, s[42:43]
	global_load_lds_dwordx4 v[120:121], off
	s_add_u32 m0, s41, 0x2000
	v_lshl_add_u64 v[120:121], v[104:105], 0, s[42:43]
	global_load_lds_dwordx4 v[120:121], off
	s_add_u32 m0, s41, 0x6000
	v_lshl_add_u64 v[120:121], v[112:113], 0, s[42:43]
	global_load_lds_dwordx4 v[120:121], off
	s_add_u32 m0, s41, 0x3000
	v_lshl_add_u64 v[120:121], v[106:107], 0, s[42:43]
	global_load_lds_dwordx4 v[120:121], off
	s_add_u32 m0, s41, 0x7000
	v_lshl_add_u64 v[120:121], v[114:115], 0, s[42:43]
	global_load_lds_dwordx4 v[120:121], off
	s_and_b32 s13, s13, 0x8000
	v_add_u32_e32 v124, s13, v116
	v_add_u32_e32 v151, v124, v117
	v_add_u32_e32 v160, v124, v118
	ds_read_b128 v[120:123], v151
	ds_read_b128 v[124:127], v160 offset:16384
	ds_read_b128 v[128:131], v151 offset:2048
	ds_read_b128 v[132:135], v160 offset:18432
	ds_read_b128 v[136:139], v151 offset:4096
	ds_read_b128 v[140:143], v160 offset:20480
	ds_read_b128 v[152:155], v151 offset:6144
	ds_read_b128 v[156:159], v160 offset:22528
	s_waitcnt lgkmcnt(0)
	v_mfma_f32_16x16x32_bf16 v[62:65], v[124:127], v[120:123], v[62:65]
	s_add_u32 s42, s42, 0x80
	s_addc_u32 s43, s43, 0
	s_cmpk_eq_i32 s42, 0x780
	v_mfma_f32_16x16x32_bf16 v[58:61], v[132:135], v[120:123], v[58:61]
	s_mov_b32 s13, s1
	v_mfma_f32_16x16x32_bf16 v[54:57], v[140:143], v[120:123], v[54:57]
	v_mfma_f32_16x16x32_bf16 v[50:53], v[156:159], v[120:123], v[50:53]
	v_mfma_f32_16x16x32_bf16 v[46:49], v[124:127], v[128:131], v[46:49]
	v_mfma_f32_16x16x32_bf16 v[42:45], v[132:135], v[128:131], v[42:45]
	v_mfma_f32_16x16x32_bf16 v[38:41], v[140:143], v[128:131], v[38:41]
	v_mfma_f32_16x16x32_bf16 v[34:37], v[156:159], v[128:131], v[34:37]
	v_mfma_f32_16x16x32_bf16 v[30:33], v[124:127], v[136:139], v[30:33]
	v_mfma_f32_16x16x32_bf16 v[26:29], v[132:135], v[136:139], v[26:29]
	v_mfma_f32_16x16x32_bf16 v[22:25], v[140:143], v[136:139], v[22:25]
	v_mfma_f32_16x16x32_bf16 v[18:21], v[156:159], v[136:139], v[18:21]
	v_mfma_f32_16x16x32_bf16 v[14:17], v[124:127], v[152:155], v[14:17]
	v_mfma_f32_16x16x32_bf16 v[10:13], v[132:135], v[152:155], v[10:13]
	v_mfma_f32_16x16x32_bf16 v[6:9], v[140:143], v[152:155], v[6:9]
	v_mfma_f32_16x16x32_bf16 v[2:5], v[156:159], v[152:155], v[2:5]
	ds_read_b128 v[120:123], v151 offset:1024
	ds_read_b128 v[124:127], v160 offset:17408
	ds_read_b128 v[128:131], v151 offset:3072
	ds_read_b128 v[132:135], v160 offset:19456
	ds_read_b128 v[136:139], v151 offset:5120
	ds_read_b128 v[140:143], v160 offset:21504
	ds_read_b128 v[152:155], v151 offset:7168
	ds_read_b128 v[156:159], v160 offset:23552
	s_waitcnt lgkmcnt(0)
	v_mfma_f32_16x16x32_bf16 v[62:65], v[124:127], v[120:123], v[62:65]
	v_mfma_f32_16x16x32_bf16 v[58:61], v[132:135], v[120:123], v[58:61]
	v_mfma_f32_16x16x32_bf16 v[54:57], v[140:143], v[120:123], v[54:57]
	v_mfma_f32_16x16x32_bf16 v[50:53], v[156:159], v[120:123], v[50:53]
	v_mfma_f32_16x16x32_bf16 v[46:49], v[124:127], v[128:131], v[46:49]
	v_mfma_f32_16x16x32_bf16 v[42:45], v[132:135], v[128:131], v[42:45]
	v_mfma_f32_16x16x32_bf16 v[38:41], v[140:143], v[128:131], v[38:41]
	v_mfma_f32_16x16x32_bf16 v[34:37], v[156:159], v[128:131], v[34:37]
	v_mfma_f32_16x16x32_bf16 v[30:33], v[124:127], v[136:139], v[30:33]
	v_mfma_f32_16x16x32_bf16 v[26:29], v[132:135], v[136:139], v[26:29]
	v_mfma_f32_16x16x32_bf16 v[22:25], v[140:143], v[136:139], v[22:25]
	v_mfma_f32_16x16x32_bf16 v[18:21], v[156:159], v[136:139], v[18:21]
	v_mfma_f32_16x16x32_bf16 v[14:17], v[124:127], v[152:155], v[14:17]
	v_mfma_f32_16x16x32_bf16 v[10:13], v[132:135], v[152:155], v[10:13]
	v_mfma_f32_16x16x32_bf16 v[6:9], v[140:143], v[152:155], v[6:9]
	v_mfma_f32_16x16x32_bf16 v[2:5], v[156:159], v[152:155], v[2:5]
	s_cbranch_scc0 .LBB0_300
	s_waitcnt vmcnt(0)
	s_waitcnt lgkmcnt(0)
	s_barrier
	v_add_u32_e32 v132, v116, v118
	v_add_u32_e32 v133, v116, v117
	ds_read_b128 v[136:139], v132 offset:53248
	ds_read_b128 v[140:143], v132 offset:54272
	ds_read_b128 v[152:155], v133 offset:32768
	ds_read_b128 v[156:159], v132 offset:49152
	ds_read_b128 v[164:167], v132 offset:51200
	ds_read_b128 v[168:171], v132 offset:55296
	ds_read_b128 v[128:131], v133 offset:34816
	ds_read_b128 v[234:237], v133 offset:36864
	ds_read_b128 v[238:241], v133 offset:38912
	ds_read_b128 v[250:253], v132 offset:52224
	s_cmp_gt_i32 s12, 63
	s_cselect_b64 s[48:49], -1, 0
	s_waitcnt lgkmcnt(7)
	v_mfma_f32_16x16x32_bf16 v[120:123], v[136:139], v[152:155], v[54:57]
	s_cmp_lt_i32 s56, 5
	s_cselect_b64 s[12:13], -1, 0
	s_nop 0
	s_waitcnt lgkmcnt(6)
	v_mfma_f32_16x16x32_bf16 v[62:65], v[156:159], v[152:155], v[62:65]
	s_and_b64 s[50:51], s[48:49], s[12:13]
	s_and_b64 vcc, exec, s[50:51]
	s_waitcnt lgkmcnt(5)
	v_mfma_f32_16x16x32_bf16 v[58:61], v[164:167], v[152:155], v[58:61]
	s_waitcnt lgkmcnt(4)
	v_mfma_f32_16x16x32_bf16 v[104:107], v[168:171], v[152:155], v[50:53]
	ds_read_b128 v[152:155], v132 offset:50176
	s_nop 2
	s_waitcnt lgkmcnt(4)
	v_mfma_f32_16x16x32_bf16 v[46:49], v[156:159], v[128:131], v[46:49]
	v_mfma_f32_16x16x32_bf16 v[42:45], v[164:167], v[128:131], v[42:45]
	v_mfma_f32_16x16x32_bf16 v[38:41], v[136:139], v[128:131], v[38:41]
	v_mfma_f32_16x16x32_bf16 v[34:37], v[168:171], v[128:131], v[34:37]
	ds_read_b128 v[128:131], v133 offset:33792
	s_waitcnt lgkmcnt(4)
	v_mfma_f32_16x16x32_bf16 v[30:33], v[156:159], v[234:237], v[30:33]
	v_mfma_f32_16x16x32_bf16 v[26:29], v[164:167], v[234:237], v[26:29]
	v_mfma_f32_16x16x32_bf16 v[22:25], v[136:139], v[234:237], v[22:25]
	v_mfma_f32_16x16x32_bf16 v[18:21], v[168:171], v[234:237], v[18:21]
	ds_read_b128 v[234:237], v132 offset:56320
	s_waitcnt lgkmcnt(4)
	v_mfma_f32_16x16x32_bf16 v[14:17], v[156:159], v[238:241], v[14:17]
	ds_read_b128 v[156:159], v133 offset:35840
	v_mfma_f32_16x16x32_bf16 v[100:103], v[164:167], v[238:241], v[10:13]
	ds_read_b128 v[164:167], v133 offset:39936
	v_mfma_f32_16x16x32_bf16 v[112:115], v[136:139], v[238:241], v[6:9]
	ds_read_b128 v[136:139], v133 offset:37888
	s_nop 2
	v_mfma_f32_16x16x32_bf16 v[124:127], v[168:171], v[238:241], v[2:5]
	s_nop 2
	s_waitcnt lgkmcnt(4)
	v_mfma_f32_16x16x32_bf16 v[54:57], v[250:253], v[128:131], v[58:61]
	v_mfma_f32_16x16x32_bf16 v[58:61], v[140:143], v[128:131], v[120:123]
	s_nop 2
	v_mfma_f32_16x16x32_bf16 v[50:53], v[152:155], v[128:131], v[62:65]
	s_waitcnt lgkmcnt(3)
	v_mfma_f32_16x16x32_bf16 v[62:65], v[234:237], v[128:131], v[104:107]
	s_nop 1
	s_waitcnt lgkmcnt(2)
	v_mfma_f32_16x16x32_bf16 v[46:49], v[152:155], v[156:159], v[46:49]
	v_mfma_f32_16x16x32_bf16 v[42:45], v[250:253], v[156:159], v[42:45]
	v_mfma_f32_16x16x32_bf16 v[38:41], v[140:143], v[156:159], v[38:41]
	v_mfma_f32_16x16x32_bf16 v[34:37], v[234:237], v[156:159], v[34:37]
	s_waitcnt lgkmcnt(0)
	v_mfma_f32_16x16x32_bf16 v[30:33], v[152:155], v[136:139], v[30:33]
	v_mfma_f32_16x16x32_bf16 v[26:29], v[250:253], v[136:139], v[26:29]
	v_mfma_f32_16x16x32_bf16 v[10:13], v[152:155], v[164:167], v[14:17]
	v_mfma_f32_16x16x32_bf16 v[6:9], v[250:253], v[164:167], v[100:103]
	v_add_u32_e32 v111, s40, v119
	s_nop 0
	v_and_b32_e32 v14, 0xfc0, v111
	v_mov_b32_e32 v15, v0
	v_mfma_f32_16x16x32_bf16 v[22:25], v[140:143], v[136:139], v[22:25]
	v_lshl_add_u64 v[100:101], v[68:69], 0, v[14:15]
	v_lshl_add_u64 v[102:103], v[70:71], 0, v[14:15]
	v_mfma_f32_16x16x32_bf16 v[18:21], v[234:237], v[136:139], v[18:21]
	v_mfma_f32_16x16x32_bf16 v[2:5], v[140:143], v[164:167], v[112:115]
	v_mfma_f32_16x16x32_bf16 v[14:17], v[234:237], v[164:167], v[124:127]
	s_cbranch_vccz .LBB0_303
	global_load_dwordx4 v[104:107], v[100:101], off
	global_load_dwordx4 v[112:115], v[102:103], off
	global_load_dwordx4 v[120:123], v[72:73], off
	global_load_dwordx4 v[124:127], v[74:75], off
	s_waitcnt vmcnt(0)
	v_mul_f32_e32 v130, v52, v106
	v_pk_mul_f32 v[108:109], v[50:51], v[112:113]
	v_pk_mul_f32 v[112:113], v[54:55], v[112:113]
	v_mul_f32_e32 v132, v56, v114
	v_mul_f32_e32 v106, v56, v106
	v_mul_f32_e32 v134, v52, v114
	v_mul_f32_e32 v136, v60, v122
	v_mul_f32_e32 v138, v64, v126
	v_mul_f32_e32 v122, v64, v122
	v_mul_f32_e32 v140, v60, v126
	v_mov_b32_e32 v56, v53
	v_mov_b32_e32 v114, v107
	v_mov_b32_e32 v52, v57
	v_mov_b32_e32 v64, v61
	v_mov_b32_e32 v126, v123
	v_mov_b32_e32 v60, v65
	v_pk_mul_f32 v[142:143], v[56:57], v[114:115]
	v_pk_mul_f32 v[52:53], v[52:53], v[114:115]
	v_pk_fma_f32 v[50:51], v[50:51], v[104:105], v[112:113] neg_lo:[0,0,1] neg_hi:[0,0,1]
	v_pk_fma_f32 v[54:55], v[54:55], v[104:105], v[108:109]
	v_pk_mul_f32 v[104:105], v[64:65], v[126:127]
	v_pk_mul_f32 v[60:61], v[60:61], v[126:127]
	v_pk_mul_f32 v[128:129], v[58:59], v[124:125]
	v_pk_mul_f32 v[124:125], v[62:63], v[124:125]
	v_mov_b32_e32 v131, v142
	v_mov_b32_e32 v133, v143
	v_mov_b32_e32 v107, v52
	v_mov_b32_e32 v135, v53
	v_mov_b32_e32 v137, v104
	v_mov_b32_e32 v139, v105
	v_mov_b32_e32 v123, v60
	v_mov_b32_e32 v141, v61
	v_pk_add_f32 v[52:53], v[130:131], v[132:133] neg_lo:[0,1] neg_hi:[0,1]
	v_pk_add_f32 v[56:57], v[106:107], v[134:135]
	v_pk_fma_f32 v[58:59], v[58:59], v[120:121], v[124:125] neg_lo:[0,0,1] neg_hi:[0,0,1]
	v_pk_add_f32 v[60:61], v[136:137], v[138:139] neg_lo:[0,1] neg_hi:[0,1]
	v_pk_fma_f32 v[62:63], v[62:63], v[120:121], v[128:129]
	v_pk_add_f32 v[64:65], v[122:123], v[140:141]
